# phase-6 (kernel tail: final RMSNorm of sample rows) de-serialised: the four final_gain loads issued up front, stores back to back; bit-identical arithmetic
# speedup vs baseline: 1.0032x; 1.0032x over previous
; DI void phase6(const Params& p, char* sm) {
;     ...
;     for (int row = NP + blockIdx.x * 4 + w; row < NT; row += gridDim.x * 4) {
;         const float* xr = xnew + (size_t)row * 1024;
;         float* yr = row < NP ? p.out + O_YP + (size_t)row * 1024 : p.out + O_YS + (size_t)(row - NP) * 1024;
;         f32x4 v[4]; float ss = 0.f;
; #pragma unroll
;         for (int j = 0; j < 4; ++j) { v[j] = *(const f32x4*)(xr + lane * 4 + 256 * j); ss += v[j].x * v[j].x + v[j].y * v[j].y + v[j].z * v[j].z + v[j].w * v[j].w; }
;         ss = wave_sum(ss);
;         const float inv = rsqrtf(ss * (1.f / 1024.f) + 1e-6f);
; #pragma unroll
;         for (int j = 0; j < 4; ++j) {
;             const f32x4 g = *(const f32x4*)(p.final_gain + lane * 4 + 256 * j);
;             f32x4 o; o.x = v[j].x * inv * g.x; o.y = v[j].y * inv * g.y; o.z = v[j].z * inv * g.z; o.w = v[j].w * inv * g.w;
;             *(f32x4*)(yr + lane * 4 + 256 * j) = o;
;         }
;     }
.LBB0_1716:
	v_add_u32_e32 v36, 0x4000, v0
	v_ashrrev_i32_e32 v37, 31, v36
	v_lshlrev_b64 v[38:39], 12, v[36:37]
	v_lshl_add_u64 v[32:33], v[2:3], 0, v[38:39]
	global_load_dwordx4 v[16:19], v[32:33], off
	global_load_dwordx4 v[20:23], v[32:33], off offset:1024
	global_load_dwordx4 v[24:27], v[32:33], off offset:2048
	global_load_dwordx4 v[28:31], v[32:33], off offset:3072
	v_lshlrev_b64 v[40:41], 12, v[0:1]
	global_load_dwordx4 v[32:35], v[4:5], off
	global_load_dwordx4 v[54:57], v[4:5], off offset:1024
	global_load_dwordx4 v[58:61], v[4:5], off offset:2048
	global_load_dwordx4 v[62:65], v[4:5], off offset:3072
	v_lshl_add_u64 v[40:41], s[0:1], 0, v[40:41]
	v_lshl_add_u64 v[38:39], s[60:61], 0, v[38:39]
	v_cmp_gt_i32_e32 vcc, s4, v36
	v_add_u32_e32 v0, s5, v0
	s_waitcnt vmcnt(4)
	v_mov_b32_e32 v42, v18
	v_cndmask_b32_e32 v37, v41, v39, vcc
	v_cndmask_b32_e32 v36, v40, v38, vcc
	v_mov_b32_e32 v40, v17
	v_mov_b32_e32 v41, v21
	v_mov_b32_e32 v38, v16
	v_mov_b32_e32 v39, v20
	v_mov_b32_e32 v48, v25
	v_mov_b32_e32 v49, v29
	v_pk_mul_f32 v[40:41], v[40:41], v[40:41]
	v_mov_b32_e32 v43, v22
	v_mov_b32_e32 v46, v24
	v_mov_b32_e32 v47, v28
	v_pk_mul_f32 v[48:49], v[48:49], v[48:49]
	v_pk_fma_f32 v[38:39], v[38:39], v[38:39], v[40:41]
	v_mov_b32_e32 v44, v19
	v_mov_b32_e32 v45, v23
	v_mov_b32_e32 v50, v26
	v_mov_b32_e32 v51, v30
	v_pk_fma_f32 v[40:41], v[46:47], v[46:47], v[48:49]
	v_pk_fma_f32 v[38:39], v[42:43], v[42:43], v[38:39]
	v_mov_b32_e32 v52, v27
	v_mov_b32_e32 v53, v31
	v_pk_fma_f32 v[40:41], v[50:51], v[50:51], v[40:41]
	v_pk_fma_f32 v[38:39], v[44:45], v[44:45], v[38:39]
	v_pk_fma_f32 v[40:41], v[52:53], v[52:53], v[40:41]
	v_add_f32_e32 v15, v38, v39
	v_add_f32_e32 v15, v15, v40
	v_add_f32_e32 v15, v15, v41
	ds_bpermute_b32 v38, v8, v15
	v_lshl_add_u64 v[36:37], v[36:37], 0, v[6:7]
	s_waitcnt lgkmcnt(0)
	v_add_f32_e32 v15, v15, v38
	ds_bpermute_b32 v38, v9, v15
	s_waitcnt lgkmcnt(0)
	v_add_f32_e32 v15, v15, v38
	ds_bpermute_b32 v38, v10, v15
	s_waitcnt lgkmcnt(0)
	v_add_f32_e32 v15, v15, v38
	ds_bpermute_b32 v38, v11, v15
	s_waitcnt lgkmcnt(0)
	v_add_f32_e32 v15, v15, v38
	ds_bpermute_b32 v38, v12, v15
	s_waitcnt lgkmcnt(0)
	v_add_f32_e32 v15, v15, v38
	ds_bpermute_b32 v38, v13, v15
	s_waitcnt lgkmcnt(0)
	v_add_f32_e32 v15, v15, v38
	v_fmamk_f32 v15, v15, 0x3a800000, v14
	v_mul_f32_e32 v38, 0x4b800000, v15
	v_cmp_gt_f32_e32 vcc, s6, v15
	s_nop 1
	v_cndmask_b32_e32 v15, v15, v38, vcc
	v_rsq_f32_e32 v15, v15
	s_nop 0
	v_mul_f32_e32 v38, 0x45800000, v15
	v_cndmask_b32_e32 v38, v15, v38, vcc
	v_pk_mul_f32 v[16:17], v[16:17], v[38:39] op_sel_hi:[1,0]
	v_pk_mul_f32 v[18:19], v[18:19], v[38:39] op_sel_hi:[1,0]
	v_pk_mul_f32 v[20:21], v[20:21], v[38:39] op_sel_hi:[1,0]
	v_pk_mul_f32 v[22:23], v[22:23], v[38:39] op_sel_hi:[1,0]
	v_pk_mul_f32 v[24:25], v[24:25], v[38:39] op_sel_hi:[1,0]
	v_pk_mul_f32 v[26:27], v[26:27], v[38:39] op_sel_hi:[1,0]
	v_pk_mul_f32 v[28:29], v[28:29], v[38:39] op_sel_hi:[1,0]
	v_pk_mul_f32 v[30:31], v[30:31], v[38:39] op_sel_hi:[1,0]
	s_waitcnt vmcnt(0)
	v_pk_mul_f32 v[16:17], v[32:33], v[16:17]
	v_pk_mul_f32 v[18:19], v[34:35], v[18:19]
	v_pk_mul_f32 v[20:21], v[54:55], v[20:21]
	v_pk_mul_f32 v[22:23], v[56:57], v[22:23]
	v_pk_mul_f32 v[24:25], v[58:59], v[24:25]
	v_pk_mul_f32 v[26:27], v[60:61], v[26:27]
	v_pk_mul_f32 v[28:29], v[62:63], v[28:29]
	v_pk_mul_f32 v[30:31], v[64:65], v[30:31]
	global_store_dwordx4 v[36:37], v[16:19], off
	global_store_dwordx4 v[36:37], v[20:23], off offset:1024
	global_store_dwordx4 v[36:37], v[24:27], off offset:2048
	global_store_dwordx4 v[36:37], v[28:31], off offset:3072
	v_add_u32_e32 v15, 0x4000, v0
	v_cmp_lt_i32_e32 vcc, s7, v15
	s_or_b64 s[2:3], vcc, s[2:3]
	s_andn2_b64 exec, exec, s[2:3]
	s_cbranch_execnz .LBB0_1716
